# first row pass no longer writes the f32 working copy of x for rows that layer 0's mix row pass handles in its fast body: that pass reads those rows from the inputs (pointer displacement), the copy is
# speedup vs baseline: 1.0186x; 1.0032x over previous
;     __device__ __forceinline__ void init(int N, int G, int c, int latent_only) { lat = latent_only; b.init(latent_only ? NB * SEQ : M, N, G, c); }
;     __device__ __forceinline__ void init(int c_, unsigned* cnt_) { lat.init(NB * SEQ, FF2, 1, 0); c = c_; cnt = cnt_; }
; __device__ __forceinline__ void row_pass(const RowPass& R, int gw, int ngw, int lane) {
;     ...
;             xrow[k] = isctx ? R.xc + ((size_t)b * CTXL + i) * DM : R.out + ((size_t)b * SEQ + (i - CTXL)) * DM;
;             const float* src = R.init ? (isctx ? R.ctx_in + ((size_t)b * CTXL + i) * DM : R.x_in + ((size_t)b * SEQ + (i - CTXL)) * DM) : xrow[k];
; __global__ void __launch_bounds__(NTHR, 2) fwd_kernel(Args A_) {
;     ...
;                 RowPass R{A->x, A->ctx, A->out, xc, Yb, Hb, modp, A->g_post_mix + l * DM, A->g_pre_ffn + l * DM, 0, 1, 1, l, 2, l, 3, l == DEPTH - 1};
;                 row_pass(R, gw, ngw, lane);
.LBB0_128:
	s_cmp_gt_i32 s84, 2
	s_mov_b64 s[4:5], -1
	s_cbranch_scc0 .LBB0_141
	s_cmp_gt_i32 s36, 0x87ff
	s_cbranch_scc1 .LBB0_140
	s_sub_i32 s3, s57, 30
	s_load_dwordx2 s[4:5], s[0:1], 0xa0
	s_load_dwordx4 s[8:11], s[0:1], 0x38
	s_cmp_lt_u32 s3, -7
	s_cselect_b64 s[62:63], -1, 0
	s_lshl_b32 s6, s12, 10
	s_ashr_i32 s7, s6, 31
	s_lshl_b64 s[6:7], s[6:7], 2
	s_waitcnt lgkmcnt(0)
	s_add_u32 s10, s10, s6
	s_addc_u32 s11, s11, s7
	s_add_u32 s6, s8, s6
	s_addc_u32 s7, s9, s7
	s_waitcnt vmcnt(0)
	v_lshlrev_b32_e32 v0, 4, v216
	v_mov_b32_e32 v1, v161
	s_ashr_i32 s37, s36, 31
	v_lshl_add_u64 v[42:43], s[6:7], 0, v[0:1]
	s_lshl_b64 s[6:7], s[36:37], 11
	s_add_u32 s6, s28, s6
	v_lshlrev_b32_e32 v160, 3, v216
	s_addc_u32 s7, s29, s7
	v_lshl_add_u64 v[44:45], s[10:11], 0, v[0:1]
	v_lshl_add_u64 v[0:1], s[6:7], 0, v[160:161]
	s_mov_b64 s[6:7], 0xa7fa600
	v_lshlrev_b32_e32 v36, 2, v216
	v_lshl_add_u64 v[38:39], s[20:21], 0, v[160:161]
	v_lshl_add_u64 v[40:41], s[60:61], 0, v[160:161]
	s_mul_i32 s3, s12, 9
	v_lshl_add_u64 v[46:47], v[0:1], 0, s[6:7]
	s_mov_b32 s93, 0
	s_mov_b32 s99, 0
	global_load_dwordx4 v[218:221], v[42:43], off
	global_load_dwordx4 v[222:225], v[42:43], off offset:1024
	global_load_dwordx4 v[226:229], v[42:43], off offset:2048
	global_load_dwordx4 v[230:233], v[42:43], off offset:3072
	global_load_dwordx4 v[234:237], v[44:45], off
	global_load_dwordx4 v[238:241], v[44:45], off offset:1024
	global_load_dwordx4 v[242:245], v[44:45], off offset:2048
	global_load_dwordx4 v[246:249], v[44:45], off offset:3072
	s_load_dwordx2 s[68:69], s[0:1], 0x0
	s_load_dwordx2 s[70:71], s[0:1], 0x10
	s_waitcnt lgkmcnt(0)
	s_sub_u32 s68, s68, s4
	s_subb_u32 s69, s69, s5
	s_sub_u32 s70, s70, s49
	s_subb_u32 s71, s71, s55
	s_cmp_eq_u32 s12, 0
	s_cselect_b32 s68, s68, 0
	s_cselect_b32 s69, s69, 0
	s_cselect_b32 s70, s70, 0
	s_cselect_b32 s71, s71, 0
	s_mov_b32 s13, s36
	s_branch .LBB0_132

;     __device__ __forceinline__ void init(int N, int G, int c, int latent_only) { lat = latent_only; b.init(latent_only ? NB * SEQ : M, N, G, c); }
;     __device__ __forceinline__ void init(int c_, unsigned* cnt_) { lat.init(NB * SEQ, FF2, 1, 0); c = c_; cnt = cnt_; }
; __device__ __forceinline__ void row_pass(const RowPass& R, int gw, int ngw, int lane) {
;     ...
;     for (int row0 = gw; row0 < M; row0 += NR * ngw) {
;         f32x4 v[NR][4]; u32x2 yw[NR][4]; bool act[NR]; float* xrow[NR]; int bbs[NR];
; #pragma unroll
;         for (int k = 0; k < NR; ++k) {
;             const int row = row0 + k * ngw;
;             const int rowc = row < M ? row : row0;
;             const int b = rowc / RPB, i = rowc - b * RPB; const bool isctx = i < CTXL;
;             act[k] = (row < M) && !(isctx && R.skip_ctx);
;             bbs[k] = isctx ? 8 : b;
;             xrow[k] = isctx ? R.xc + ((size_t)b * CTXL + i) * DM : R.out + ((size_t)b * SEQ + (i - CTXL)) * DM;
;             const float* src = R.init ? (isctx ? R.ctx_in + ((size_t)b * CTXL + i) * DM : R.x_in + ((size_t)b * SEQ + (i - CTXL)) * DM) : xrow[k];
;             if (act[k]) {
; #pragma unroll
;                 for (int j = 0; j < 4; ++j) v[k][j] = __builtin_nontemporal_load((const f32x4*)(src + lane * 4 + 256 * j));
;                 if (R.update) { const bf16* yr = R.Y + (size_t)rowc * DM;
; #pragma unroll
;                     for (int j = 0; j < 4; ++j) yw[k][j] = __builtin_nontemporal_load((const u32x2*)(yr + lane * 4 + 256 * j)); }
;             }
.LBB0_132:
	s_mul_hi_i32 s6, s13, 0x78787879
	s_lshr_b32 s7, s6, 31
	s_ashr_i32 s6, s6, 11
	s_add_i32 s6, s6, s7
	s_mul_i32 s7, s6, 0xffffef00
	s_add_i32 s7, s13, s7
	s_cmpk_gt_i32 s7, 0xff
	s_cselect_b64 s[50:51], -1, 0
	s_add_i32 s8, s44, s13
	s_cmp_lt_i32 s8, 0x8800
	s_cbranch_scc0 .Lr2_slow
	s_mul_hi_i32 s9, s8, 0x78787879
	s_lshr_b32 s25, s9, 31
	s_ashr_i32 s9, s9, 11
	s_add_i32 s9, s9, s25
	s_mul_i32 s25, s9, 0xffffef00
	s_add_i32 s25, s8, s25
	s_cmpk_gt_i32 s25, 0xff
	s_cselect_b64 s[52:53], -1, 0
	s_and_b64 s[46:47], s[50:51], s[52:53]
	s_or_b64 s[46:47], s[46:47], s[62:63]
	s_cmp_lg_u64 s[46:47], 0
	s_cbranch_scc0 .Lr2_slow
	v_lshlrev_b32_e32 v160, 2, v36
	s_add_i32 s72, s7, 0xffffff00
	s_cmp_lg_u64 s[50:51], 0
	s_cselect_b32 s27, s4, s49
	s_cselect_b32 s32, s5, s55
	s_cselect_b32 s37, 24, 20
	s_cselect_b32 s72, s72, s7
	s_cselect_b32 s85, s6, 8
	s_mov_b32 s40, s6
	s_mov_b32 s41, 0
	s_lshl_b64 s[40:41], s[40:41], s37
	s_add_u32 s40, s27, s40
	s_addc_u32 s41, s32, s41
	s_lshl_b32 s72, s72, 12
	s_add_u32 s40, s40, s72
	s_addc_u32 s41, s41, 0
	s_add_i32 s27, s85, s3
	s_mul_hi_i32 s32, s27, 0x6000
	s_mulk_i32 s27, 0x6000
	s_add_u32 s66, s34, s27
	s_addc_u32 s67, s35, s32
	s_add_u32 s66, s66, 0x2000
	s_addc_u32 s67, s67, 0
	s_add_i32 s27, s85, s3
	s_mul_hi_i32 s32, s27, 0x6000
	s_mulk_i32 s27, 0x6000
	s_add_u32 s38, s34, s27
	s_addc_u32 s39, s35, s32
	s_add_u32 s38, s38, 0x3000
	s_addc_u32 s39, s39, 0
	s_add_u32 s46, s38, 0x1000
	s_addc_u32 s47, s39, 0
	s_cmp_eq_u32 s12, 0
	s_cbranch_scc1 .Lr2_slow_keepd
	s_mov_b64 s[68:69], 0
	s_mov_b64 s[70:71], 0
.Lr2_slow_keepd:
	s_cmp_lg_u64 s[50:51], 0
	s_cselect_b32 s22, s68, s70
	s_cselect_b32 s23, s69, s71
	s_add_u32 s22, s22, s40
	s_addc_u32 s23, s23, s41
	s_cmp_lg_u32 s99, 0
	s_cbranch_scc1 .Lr2_slow_pfa
	global_load_dwordx4 v[12:15], v160, s[22:23] nt
	global_load_dwordx4 v[8:11], v160, s[22:23] offset:1024 nt
	global_load_dwordx4 v[4:7], v160, s[22:23] offset:2048 nt
	global_load_dwordx4 v[0:3], v160, s[22:23] offset:3072 nt
	global_load_dwordx2 v[54:55], v[46:47], off offset:-1536 nt
	global_load_dwordx2 v[52:53], v[46:47], off offset:-1024 nt
	global_load_dwordx2 v[50:51], v[46:47], off offset:-512 nt
	global_load_dwordx2 v[48:49], v[46:47], off nt
.Lr2_slow_pfa:
	s_mov_b32 s6, s8
	s_ashr_i32 s7, s8, 31
	s_lshl_b64 s[6:7], s[6:7], 11
	v_lshl_add_u64 v[250:251], v[38:39], 0, s[6:7]
	v_lshl_add_u64 v[252:253], v[40:41], 0, s[6:7]
	s_mov_b64 s[6:7], s[52:53]
	s_add_i32 s72, s25, 0xffffff00
	s_cmp_lg_u64 s[6:7], 0
	s_cselect_b32 s27, s4, s49
	s_cselect_b32 s32, s5, s55
	s_cselect_b32 s37, 24, 20
	s_cselect_b32 s72, s72, s25
	s_cselect_b32 s85, s9, 8
	s_mov_b32 s64, s9
	s_mov_b32 s65, 0
	s_lshl_b64 s[64:65], s[64:65], s37
	s_add_u32 s64, s27, s64
	s_addc_u32 s65, s32, s65
	s_lshl_b32 s72, s72, 12
	s_add_u32 s64, s64, s72
	s_addc_u32 s65, s65, 0
	s_add_i32 s27, s85, s3
	s_mul_hi_i32 s32, s27, 0x6000
	s_mulk_i32 s27, 0x6000
	s_add_u32 s10, s34, s27
	s_addc_u32 s11, s35, s32
	s_add_u32 s10, s10, 0x2000
	s_addc_u32 s11, s11, 0
	s_add_i32 s27, s85, s3
	s_mul_hi_i32 s32, s27, 0x6000
	s_mulk_i32 s27, 0x6000
	s_add_u32 s50, s34, s27
	s_addc_u32 s51, s35, s32
	s_add_u32 s50, s50, 0x3000
	s_addc_u32 s51, s51, 0
	s_add_u32 s52, s50, 0x1000
	s_addc_u32 s53, s51, 0
	s_cmp_lg_u64 s[6:7], 0
	s_cselect_b32 s22, s68, s70
	s_cselect_b32 s23, s69, s71
	s_add_u32 s22, s22, s64
	s_addc_u32 s23, s23, s65
	s_cmp_lg_u32 s99, 0
	s_cbranch_scc1 .Lr2_slow_pf
	s_and_b32 s72, s13, 7
	s_and_b32 s85, s72, 3
	s_lshl_b32 s85, s85, 10
	s_lshl_b32 s37, s72, 10
	s_add_i32 s37, s37, s93
	s_cmp_lt_u32 s72, 4
	s_cselect_b32 s6, s66, s38
	s_cselect_b32 s7, s67, s39
	s_cselect_b32 s8, s46, s10
	s_cselect_b32 s9, s47, s11
	s_cselect_b32 s26, s50, s52
	s_cselect_b32 s27, s51, s53
	s_add_u32 s6, s6, s85
	s_addc_u32 s7, s7, 0
	s_add_u32 s8, s8, s85
	s_addc_u32 s9, s9, 0
	s_add_u32 s26, s26, s85
	s_addc_u32 s27, s27, 0
	s_mov_b32 m0, s37
	s_nop 0
	global_load_lds_dwordx4 v160, s[6:7]
	s_add_i32 s37, s37, 0x2000
	s_mov_b32 m0, s37
	s_nop 0
	global_load_lds_dwordx4 v160, s[8:9]
	s_add_i32 s37, s37, 0x2000
	s_mov_b32 m0, s37
	s_nop 0
	global_load_lds_dwordx4 v160, s[26:27]
	global_load_dwordx4 v[16:19], v160, s[22:23] nt
	global_load_dwordx4 v[20:23], v160, s[22:23] offset:1024 nt
	global_load_dwordx4 v[24:27], v160, s[22:23] offset:2048 nt
	global_load_dwordx4 v[28:31], v160, s[22:23] offset:3072 nt
	global_load_dwordx2 v[62:63], v[250:251], off nt
	global_load_dwordx2 v[60:61], v[250:251], off offset:512 nt
	global_load_dwordx2 v[58:59], v[250:251], off offset:1024 nt
	global_load_dwordx2 v[56:57], v[250:251], off offset:1536 nt
	s_waitcnt vmcnt(8)
	s_branch .Lr2_slow_proc
.Lr2_slow_pf:
	global_load_dwordx4 v[16:19], v160, s[22:23] nt
	global_load_dwordx4 v[20:23], v160, s[22:23] offset:1024 nt
	global_load_dwordx4 v[24:27], v160, s[22:23] offset:2048 nt
	global_load_dwordx4 v[28:31], v160, s[22:23] offset:3072 nt
	global_load_dwordx2 v[62:63], v[250:251], off nt
	global_load_dwordx2 v[60:61], v[250:251], off offset:512 nt
	global_load_dwordx2 v[58:59], v[250:251], off offset:1024 nt
	global_load_dwordx2 v[56:57], v[250:251], off offset:1536 nt
	s_waitcnt vmcnt(16)
; __device__ __forceinline__ unsigned pk2(float lo, float hi) { return pg8::cvt_pk_bf16(lo, hi); }
; __device__ __forceinline__ float bflo(unsigned w) { return __uint_as_float(w << 16); }
; __device__ __forceinline__ float bfhi(unsigned w) { return __uint_as_float(w & 0xffff0000u); }
; __device__ __forceinline__ void row_pass(const RowPass& R, int gw, int ngw, int lane) {
;     ...
;             if (R.update) {
;                 f32x4 y[4]; float ss = 0.f;
; #pragma unroll
;                 for (int j = 0; j < 4; ++j) { const u32x2 w = yw[k][j]; y[j] = (f32x4){bflo(w.x), bfhi(w.x), bflo(w.y), bfhi(w.y)};
;                     ss += (y[j][0] * y[j][0] + y[j][1] * y[j][1]) + (y[j][2] * y[j][2] + y[j][3] * y[j][3]); }
;                 const float rstd = __builtin_amdgcn_rsqf(wave_sum(ss) * (1.0f / DM) + EPS);
;                 const float* gate = R.mod + ((size_t)(R.lg * 9 + bb) * NMOD + R.gi) * DM;
; #pragma unroll
;                 for (int j = 0; j < 4; ++j) { const f32x4 g = *(const f32x4*)(gate + lane * 4 + 256 * j), gp = *(const f32x4*)(R.gpost + lane * 4 + 256 * j);
;                     v[k][j] = v[k][j] + g * (y[j] * rstd * gp); }
;             }
;             if (R.init || R.update) {
; #pragma unroll
;                 for (int j = 0; j < 4; ++j) __builtin_nontemporal_store(v[k][j], (f32x4*)(xrow[k] + lane * 4 + 256 * j));
;             }
;             if (R.norm_out) {
;                 float ss = 0.f;
; #pragma unroll
;                 for (int j = 0; j < 4; ++j) ss += (v[k][j][0] * v[k][j][0] + v[k][j][1] * v[k][j][1]) + (v[k][j][2] * v[k][j][2] + v[k][j][3] * v[k][j][3]);
;                 const float rstd = __builtin_amdgcn_rsqf(wave_sum(ss) * (1.0f / DM) + EPS);
;                 const float* shift = R.mod + ((size_t)(R.ln * 9 + bb) * NMOD + R.si) * DM; const float* scale = shift + DM;
;                 bf16* hr = R.H + (size_t)row * DM;
; #pragma unroll
;                 for (int j = 0; j < 4; ++j) { const f32x4 gp = *(const f32x4*)(R.gpre + lane * 4 + 256 * j), sh = *(const f32x4*)(shift + lane * 4 + 256 * j), sc = *(const f32x4*)(scale + lane * 4 + 256 * j);
;                     const f32x4 hv = (v[k][j] * rstd * gp) * (sc + 1.0f) + sh;
;                     u32x2 w; w.x = pk2(hv[0], hv[1]); w.y = pk2(hv[2], hv[3]); *(u32x2*)(hr + lane * 4 + 256 * j) = w; }
;             }
.Lr2_slow_proc:
	s_barrier
	v_add_u32_e32 v37, s93, v160
	ds_read_b128 v[64:67], v37
	ds_read_b128 v[68:71], v37 offset:1024
	ds_read_b128 v[72:75], v37 offset:2048
	ds_read_b128 v[76:79], v37 offset:3072
	ds_read_b128 v[80:83], v37 offset:4096
	ds_read_b128 v[84:87], v37 offset:5120
	ds_read_b128 v[88:91], v37 offset:6144
	ds_read_b128 v[92:95], v37 offset:7168
	v_lshlrev_b32_e32 v172, 16, v54
	v_and_b32_e32 v173, 0xffff0000, v54
	v_lshlrev_b32_e32 v174, 16, v55
	v_and_b32_e32 v175, 0xffff0000, v55
	v_pk_mul_f32 v[166:167], v[172:173], v[172:173]
	v_pk_mul_f32 v[168:169], v[174:175], v[174:175]
	v_lshlrev_b32_e32 v176, 16, v52
	v_and_b32_e32 v177, 0xffff0000, v52
	v_lshlrev_b32_e32 v178, 16, v53
	v_and_b32_e32 v179, 0xffff0000, v53
	v_pk_fma_f32 v[166:167], v[176:177], v[176:177], v[166:167]
	v_pk_fma_f32 v[168:169], v[178:179], v[178:179], v[168:169]
	v_lshlrev_b32_e32 v180, 16, v50
	v_and_b32_e32 v181, 0xffff0000, v50
	v_lshlrev_b32_e32 v182, 16, v51
	v_and_b32_e32 v183, 0xffff0000, v51
	v_pk_fma_f32 v[166:167], v[180:181], v[180:181], v[166:167]
	v_pk_fma_f32 v[168:169], v[182:183], v[182:183], v[168:169]
	v_lshlrev_b32_e32 v184, 16, v48
	v_and_b32_e32 v185, 0xffff0000, v48
	v_lshlrev_b32_e32 v186, 16, v49
	v_and_b32_e32 v187, 0xffff0000, v49
	v_pk_fma_f32 v[166:167], v[184:185], v[184:185], v[166:167]
	v_pk_fma_f32 v[168:169], v[186:187], v[186:187], v[168:169]
	v_pk_add_f32 v[166:167], v[166:167], v[168:169]
	s_nop 0
	v_add_f32_e32 v164, v166, v167
	v_mov_b32_e32 v165, v164
	s_nop 1
	v_permlane32_swap_b32_e32 v165, v164
	v_add_f32_e32 v164, v164, v165
	v_mov_b32_e32 v165, v164
	s_nop 1
	v_permlane16_swap_b32_e32 v165, v164
	v_add_f32_e32 v164, v164, v165
	s_nop 1
	v_add_f32_dpp v164, v164, v164 row_ror:8 row_mask:0xf bank_mask:0xf
	s_nop 1
	v_add_f32_dpp v164, v164, v164 row_ror:4 row_mask:0xf bank_mask:0xf
	s_nop 1
	v_add_f32_dpp v164, v164, v164 row_ror:2 row_mask:0xf bank_mask:0xf
	s_nop 1
	v_add_f32_dpp v164, v164, v164 row_ror:1 row_mask:0xf bank_mask:0xf
	s_nop 0
	v_fmamk_f32 v164, v164, 0x3a800000, v200
	v_rsq_f32_e32 v164, v164
	s_nop 0
	v_pk_mul_f32 v[172:173], v[172:173], v[164:165] op_sel_hi:[1,0]
	v_pk_mul_f32 v[174:175], v[174:175], v[164:165] op_sel_hi:[1,0]
	v_pk_mul_f32 v[172:173], v[218:219], v[172:173]
	v_pk_mul_f32 v[174:175], v[220:221], v[174:175]
	s_waitcnt lgkmcnt(7)
	v_pk_fma_f32 v[12:13], v[64:65], v[172:173], v[12:13]
	v_pk_fma_f32 v[14:15], v[66:67], v[174:175], v[14:15]
	global_store_dwordx4 v160, v[12:15], s[40:41] nt
	v_pk_mul_f32 v[176:177], v[176:177], v[164:165] op_sel_hi:[1,0]
	v_pk_mul_f32 v[178:179], v[178:179], v[164:165] op_sel_hi:[1,0]
	v_pk_mul_f32 v[176:177], v[222:223], v[176:177]
	v_pk_mul_f32 v[178:179], v[224:225], v[178:179]
	s_waitcnt lgkmcnt(6)
	v_pk_fma_f32 v[8:9], v[68:69], v[176:177], v[8:9]
	v_pk_fma_f32 v[10:11], v[70:71], v[178:179], v[10:11]
	global_store_dwordx4 v160, v[8:11], s[40:41] offset:1024 nt
	v_pk_mul_f32 v[180:181], v[180:181], v[164:165] op_sel_hi:[1,0]
	v_pk_mul_f32 v[182:183], v[182:183], v[164:165] op_sel_hi:[1,0]
	v_pk_mul_f32 v[180:181], v[226:227], v[180:181]
	v_pk_mul_f32 v[182:183], v[228:229], v[182:183]
	s_waitcnt lgkmcnt(5)
	v_pk_fma_f32 v[4:5], v[72:73], v[180:181], v[4:5]
	v_pk_fma_f32 v[6:7], v[74:75], v[182:183], v[6:7]
	global_store_dwordx4 v160, v[4:7], s[40:41] offset:2048 nt
	v_pk_mul_f32 v[184:185], v[184:185], v[164:165] op_sel_hi:[1,0]
	v_pk_mul_f32 v[186:187], v[186:187], v[164:165] op_sel_hi:[1,0]
	v_pk_mul_f32 v[184:185], v[230:231], v[184:185]
	v_pk_mul_f32 v[186:187], v[232:233], v[186:187]
	s_waitcnt lgkmcnt(4)
	v_pk_fma_f32 v[0:1], v[76:77], v[184:185], v[0:1]
	v_pk_fma_f32 v[2:3], v[78:79], v[186:187], v[2:3]
	global_store_dwordx4 v160, v[0:3], s[40:41] offset:3072 nt
	s_waitcnt lgkmcnt(0)
	ds_read_b128 v[172:175], v37 offset:8192
	ds_read_b128 v[176:179], v37 offset:9216
	ds_read_b128 v[180:183], v37 offset:10240
	ds_read_b128 v[184:187], v37 offset:11264
	ds_read_b128 v[188:191], v37 offset:12288
	ds_read_b128 v[192:195], v37 offset:13312
	ds_read_b128 v[196:199], v37 offset:14336
	ds_read_b128 v[96:99], v37 offset:15360
	ds_read_b128 v[64:67], v37 offset:16384
	ds_read_b128 v[68:71], v37 offset:17408
	ds_read_b128 v[72:75], v37 offset:18432
	ds_read_b128 v[76:79], v37 offset:19456
	v_add_co_u32_e32 v250, vcc, 0xfbc00000, v46
	v_addc_co_u32_e32 v251, vcc, -1, v47, vcc
	v_pk_mul_f32 v[166:167], v[12:13], v[12:13]
	v_pk_mul_f32 v[168:169], v[14:15], v[14:15]
	v_pk_fma_f32 v[166:167], v[8:9], v[8:9], v[166:167]
	v_pk_fma_f32 v[168:169], v[10:11], v[10:11], v[168:169]
	v_pk_fma_f32 v[166:167], v[4:5], v[4:5], v[166:167]
	v_pk_fma_f32 v[168:169], v[6:7], v[6:7], v[168:169]
	v_pk_fma_f32 v[166:167], v[0:1], v[0:1], v[166:167]
	v_pk_fma_f32 v[168:169], v[2:3], v[2:3], v[168:169]
	v_pk_add_f32 v[166:167], v[166:167], v[168:169]
	s_nop 0
	v_add_f32_e32 v164, v166, v167
	v_mov_b32_e32 v165, v164
	s_nop 1
	v_permlane32_swap_b32_e32 v165, v164
	v_add_f32_e32 v164, v164, v165
	v_mov_b32_e32 v165, v164
	s_nop 1
	v_permlane16_swap_b32_e32 v165, v164
	v_add_f32_e32 v164, v164, v165
	s_nop 1
	v_add_f32_dpp v164, v164, v164 row_ror:8 row_mask:0xf bank_mask:0xf
	s_nop 1
	v_add_f32_dpp v164, v164, v164 row_ror:4 row_mask:0xf bank_mask:0xf
	s_nop 1
	v_add_f32_dpp v164, v164, v164 row_ror:2 row_mask:0xf bank_mask:0xf
	s_nop 1
	v_add_f32_dpp v164, v164, v164 row_ror:1 row_mask:0xf bank_mask:0xf
	s_nop 0
	v_fmamk_f32 v164, v164, 0x3a800000, v200
	v_rsq_f32_e32 v164, v164
	s_nop 0
	v_pk_mul_f32 v[12:13], v[12:13], v[164:165] op_sel_hi:[1,0]
	v_pk_mul_f32 v[14:15], v[14:15], v[164:165] op_sel_hi:[1,0]
	v_pk_mul_f32 v[12:13], v[234:235], v[12:13]
	v_pk_mul_f32 v[14:15], v[236:237], v[14:15]
	s_waitcnt lgkmcnt(11)
; __device__ __forceinline__ unsigned pk2(float lo, float hi) { return pg8::cvt_pk_bf16(lo, hi); }
; __device__ __forceinline__ void row_pass(const RowPass& R, int gw, int ngw, int lane) {
;     ...
;     for (int row0 = gw; row0 < M; row0 += NR * ngw) {
;         f32x4 v[NR][4]; u32x2 yw[NR][4]; bool act[NR]; float* xrow[NR]; int bbs[NR];
; #pragma unroll
;         for (int k = 0; k < NR; ++k) {
;             const int row = row0 + k * ngw;
;             const int rowc = row < M ? row : row0;
;             const int b = rowc / RPB, i = rowc - b * RPB; const bool isctx = i < CTXL;
;             act[k] = (row < M) && !(isctx && R.skip_ctx);
;             bbs[k] = isctx ? 8 : b;
;             xrow[k] = isctx ? R.xc + ((size_t)b * CTXL + i) * DM : R.out + ((size_t)b * SEQ + (i - CTXL)) * DM;
;             const float* src = R.init ? (isctx ? R.ctx_in + ((size_t)b * CTXL + i) * DM : R.x_in + ((size_t)b * SEQ + (i - CTXL)) * DM) : xrow[k];
;             if (act[k]) {
; #pragma unroll
;                 for (int j = 0; j < 4; ++j) v[k][j] = __builtin_nontemporal_load((const f32x4*)(src + lane * 4 + 256 * j));
;                 if (R.update) { const bf16* yr = R.Y + (size_t)rowc * DM;
; #pragma unroll
;                     for (int j = 0; j < 4; ++j) yw[k][j] = __builtin_nontemporal_load((const u32x2*)(yr + lane * 4 + 256 * j)); }
;             }
;     ...
;             if (R.norm_out) {
;                 float ss = 0.f;
; #pragma unroll
;                 for (int j = 0; j < 4; ++j) ss += (v[k][j][0] * v[k][j][0] + v[k][j][1] * v[k][j][1]) + (v[k][j][2] * v[k][j][2] + v[k][j][3] * v[k][j][3]);
;                 const float rstd = __builtin_amdgcn_rsqf(wave_sum(ss) * (1.0f / DM) + EPS);
;                 const float* shift = R.mod + ((size_t)(R.ln * 9 + bb) * NMOD + R.si) * DM; const float* scale = shift + DM;
;                 bf16* hr = R.H + (size_t)row * DM;
; #pragma unroll
;                 for (int j = 0; j < 4; ++j) { const f32x4 gp = *(const f32x4*)(R.gpre + lane * 4 + 256 * j), sh = *(const f32x4*)(shift + lane * 4 + 256 * j), sc = *(const f32x4*)(scale + lane * 4 + 256 * j);
;                     const f32x4 hv = (v[k][j] * rstd * gp) * (sc + 1.0f) + sh;
;                     u32x2 w; w.x = pk2(hv[0], hv[1]); w.y = pk2(hv[2], hv[3]); *(u32x2*)(hr + lane * 4 + 256 * j) = w; }
;             }
	v_pk_add_f32 v[172:173], v[172:173], 1.0 op_sel_hi:[1,0]
	v_pk_add_f32 v[174:175], v[174:175], 1.0 op_sel_hi:[1,0]
	v_pk_fma_f32 v[12:13], v[172:173], v[12:13], v[80:81]
	v_pk_fma_f32 v[14:15], v[174:175], v[14:15], v[82:83]
	v_cvt_pk_bf16_f32 v12, v12, v13
	v_cvt_pk_bf16_f32 v13, v14, v15
	global_store_dwordx2 v[250:251], v[12:13], off offset:-1536
	ds_read_b128 v[80:83], v37 offset:20480
	v_pk_mul_f32 v[8:9], v[8:9], v[164:165] op_sel_hi:[1,0]
	v_pk_mul_f32 v[10:11], v[10:11], v[164:165] op_sel_hi:[1,0]
	v_pk_mul_f32 v[8:9], v[238:239], v[8:9]
	v_pk_mul_f32 v[10:11], v[240:241], v[10:11]
	s_waitcnt lgkmcnt(11)
	v_pk_add_f32 v[176:177], v[176:177], 1.0 op_sel_hi:[1,0]
	v_pk_add_f32 v[178:179], v[178:179], 1.0 op_sel_hi:[1,0]
	v_pk_fma_f32 v[8:9], v[176:177], v[8:9], v[84:85]
	v_pk_fma_f32 v[10:11], v[178:179], v[10:11], v[86:87]
	v_cvt_pk_bf16_f32 v8, v8, v9
	v_cvt_pk_bf16_f32 v9, v10, v11
	global_store_dwordx2 v[250:251], v[8:9], off offset:-1024
	ds_read_b128 v[84:87], v37 offset:21504
	v_pk_mul_f32 v[4:5], v[4:5], v[164:165] op_sel_hi:[1,0]
	v_pk_mul_f32 v[6:7], v[6:7], v[164:165] op_sel_hi:[1,0]
	v_pk_mul_f32 v[4:5], v[242:243], v[4:5]
	v_pk_mul_f32 v[6:7], v[244:245], v[6:7]
	s_waitcnt lgkmcnt(11)
	v_pk_add_f32 v[180:181], v[180:181], 1.0 op_sel_hi:[1,0]
	v_pk_add_f32 v[182:183], v[182:183], 1.0 op_sel_hi:[1,0]
	v_pk_fma_f32 v[4:5], v[180:181], v[4:5], v[88:89]
	v_pk_fma_f32 v[6:7], v[182:183], v[6:7], v[90:91]
	v_cvt_pk_bf16_f32 v4, v4, v5
	v_cvt_pk_bf16_f32 v5, v6, v7
	global_store_dwordx2 v[250:251], v[4:5], off offset:-512
	ds_read_b128 v[88:91], v37 offset:22528
	v_pk_mul_f32 v[0:1], v[0:1], v[164:165] op_sel_hi:[1,0]
	v_pk_mul_f32 v[2:3], v[2:3], v[164:165] op_sel_hi:[1,0]
	v_pk_mul_f32 v[0:1], v[246:247], v[0:1]
	v_pk_mul_f32 v[2:3], v[248:249], v[2:3]
	s_waitcnt lgkmcnt(11)
	v_pk_add_f32 v[184:185], v[184:185], 1.0 op_sel_hi:[1,0]
	v_pk_add_f32 v[186:187], v[186:187], 1.0 op_sel_hi:[1,0]
	v_pk_fma_f32 v[0:1], v[184:185], v[0:1], v[92:93]
	v_pk_fma_f32 v[2:3], v[186:187], v[2:3], v[94:95]
	v_cvt_pk_bf16_f32 v0, v0, v1
	v_cvt_pk_bf16_f32 v1, v2, v3
	global_store_dwordx2 v[250:251], v[0:1], off
	ds_read_b128 v[92:95], v37 offset:23552
	s_waitcnt vmcnt(8)
	s_mov_b32 s99, 0
	s_add_i32 s72, s13, s48
	s_cmp_gt_i32 s72, 0x87ff
	s_cbranch_scc1 .Lr2_slow_nopf
	s_add_i32 s8, s44, s72
	s_cmp_lt_i32 s8, 0x8800
	s_cbranch_scc0 .Lr2_slow_nopf
	s_mov_b32 s41, s72
	s_mul_hi_i32 s6, s41, 0x78787879
	s_lshr_b32 s7, s6, 31
	s_ashr_i32 s6, s6, 11
	s_add_i32 s6, s6, s7
	s_mul_i32 s7, s6, 0xffffef00
	s_add_i32 s7, s41, s7
	s_cmpk_gt_i32 s7, 0xff
	s_cselect_b64 s[50:51], -1, 0
	s_mul_hi_i32 s9, s8, 0x78787879
	s_lshr_b32 s25, s9, 31
	s_ashr_i32 s9, s9, 11
	s_add_i32 s9, s9, s25
	s_mul_i32 s25, s9, 0xffffef00
	s_add_i32 s25, s8, s25
	s_cmpk_gt_i32 s25, 0xff
	s_cselect_b64 s[52:53], -1, 0
	s_and_b64 s[46:47], s[50:51], s[52:53]
	s_or_b64 s[46:47], s[46:47], s[62:63]
	s_cmp_lg_u64 s[46:47], 0
	s_cbranch_scc0 .Lr2_slow_nopf
	s_add_i32 s72, s7, 0xffffff00
	s_cmp_lg_u64 s[50:51], 0
	s_cselect_b32 s27, s4, s49
	s_cselect_b32 s32, s5, s55
	s_cselect_b32 s37, 24, 20
	s_cselect_b32 s72, s72, s7
	s_cselect_b32 s85, s6, 8
	s_mov_b32 s40, s6
	s_mov_b32 s41, 0
	s_lshl_b64 s[40:41], s[40:41], s37
	s_add_u32 s40, s27, s40
	s_addc_u32 s41, s32, s41
	s_lshl_b32 s72, s72, 12
	s_add_u32 s40, s40, s72
	s_addc_u32 s41, s41, 0
	s_add_i32 s27, s85, s3
	s_mul_hi_i32 s32, s27, 0x6000
	s_mulk_i32 s27, 0x6000
	s_add_u32 s66, s34, s27
	s_addc_u32 s67, s35, s32
	s_add_u32 s66, s66, 0x2000
	s_addc_u32 s67, s67, 0
	s_add_i32 s27, s85, s3
	s_mul_hi_i32 s32, s27, 0x6000
	s_mulk_i32 s27, 0x6000
	s_add_u32 s38, s34, s27
	s_addc_u32 s39, s35, s32
	s_add_u32 s38, s38, 0x3000
	s_addc_u32 s39, s39, 0
	s_add_u32 s46, s38, 0x1000
	s_addc_u32 s47, s39, 0
	s_cmp_lg_u64 s[50:51], 0
	s_cselect_b32 s22, s68, s70
	s_cselect_b32 s23, s69, s71
	s_add_u32 s22, s22, s40
	s_addc_u32 s23, s23, s41
	s_mov_b64 s[6:7], s[52:53]
	s_cmp_lg_u64 s[6:7], 0
	s_cselect_b32 s85, s9, 8
	s_add_i32 s27, s85, s3
	s_mul_hi_i32 s32, s27, 0x6000
	s_mulk_i32 s27, 0x6000
	s_add_u32 s10, s34, s27
	s_addc_u32 s11, s35, s32
	s_add_u32 s10, s10, 0x2000
	s_addc_u32 s11, s11, 0
	s_add_i32 s27, s85, s3
	s_mul_hi_i32 s32, s27, 0x6000
	s_mulk_i32 s27, 0x6000
	s_add_u32 s50, s34, s27
	s_addc_u32 s51, s35, s32
	s_add_u32 s50, s50, 0x3000
	s_addc_u32 s51, s51, 0
	s_add_u32 s52, s50, 0x1000
	s_addc_u32 s53, s51, 0
	s_xor_b32 s25, s93, 0x6000
	v_lshl_add_u64 v[250:251], v[46:47], 0, s[74:75]
	global_load_dwordx4 v[12:15], v160, s[22:23] nt
	global_load_dwordx4 v[8:11], v160, s[22:23] offset:1024 nt
	global_load_dwordx4 v[4:7], v160, s[22:23] offset:2048 nt
	global_load_dwordx4 v[0:3], v160, s[22:23] offset:3072 nt
	global_load_dwordx2 v[54:55], v[250:251], off offset:-1536 nt
	global_load_dwordx2 v[52:53], v[250:251], off offset:-1024 nt
	global_load_dwordx2 v[50:51], v[250:251], off offset:-512 nt
	global_load_dwordx2 v[48:49], v[250:251], off nt
	s_and_b32 s72, s13, 7
	s_and_b32 s85, s72, 3
	s_lshl_b32 s85, s85, 10
	s_lshl_b32 s37, s72, 10
	s_add_i32 s37, s37, s25
	s_cmp_lt_u32 s72, 4
	s_cselect_b32 s6, s66, s38
	s_cselect_b32 s7, s67, s39
	s_cselect_b32 s8, s46, s10
	s_cselect_b32 s9, s47, s11
	s_cselect_b32 s26, s50, s52
	s_cselect_b32 s27, s51, s53
	s_add_u32 s6, s6, s85
	s_addc_u32 s7, s7, 0
	s_add_u32 s8, s8, s85
	s_addc_u32 s9, s9, 0
	s_add_u32 s26, s26, s85
	s_addc_u32 s27, s27, 0
	s_mov_b32 m0, s37
	s_nop 0
	global_load_lds_dwordx4 v160, s[6:7]
	s_add_i32 s37, s37, 0x2000
	s_mov_b32 m0, s37
	s_nop 0
	global_load_lds_dwordx4 v160, s[8:9]
	s_add_i32 s37, s37, 0x2000
	s_mov_b32 m0, s37
	s_nop 0
	global_load_lds_dwordx4 v160, s[26:27]
	s_mov_b32 s99, 1

;     __device__ __forceinline__ void init(int N, int G, int c, int latent_only) { lat = latent_only; b.init(latent_only ? NB * SEQ : M, N, G, c); }
;     __device__ __forceinline__ void init(int c_, unsigned* cnt_) { lat.init(NB * SEQ, FF2, 1, 0); c = c_; cnt = cnt_; }
; __device__ __forceinline__ void row_pass(const RowPass& R, int gw, int ngw, int lane) {
;     ...
;     for (int row0 = gw; row0 < M; row0 += NR * ngw) {
;         f32x4 v[NR][4]; u32x2 yw[NR][4]; bool act[NR]; float* xrow[NR]; int bbs[NR];
; #pragma unroll
;         for (int k = 0; k < NR; ++k) {
;             const int row = row0 + k * ngw;
;             const int rowc = row < M ? row : row0;
;             const int b = rowc / RPB, i = rowc - b * RPB; const bool isctx = i < CTXL;
;             act[k] = (row < M) && !(isctx && R.skip_ctx);
;             bbs[k] = isctx ? 8 : b;
;             xrow[k] = isctx ? R.xc + ((size_t)b * CTXL + i) * DM : R.out + ((size_t)b * SEQ + (i - CTXL)) * DM;
;             const float* src = R.init ? (isctx ? R.ctx_in + ((size_t)b * CTXL + i) * DM : R.x_in + ((size_t)b * SEQ + (i - CTXL)) * DM) : xrow[k];
;             if (act[k]) {
; #pragma unroll
;                 for (int j = 0; j < 4; ++j) v[k][j] = __builtin_nontemporal_load((const f32x4*)(src + lane * 4 + 256 * j));
;                 if (R.update) { const bf16* yr = R.Y + (size_t)rowc * DM;
; #pragma unroll
;                     for (int j = 0; j < 4; ++j) yw[k][j] = __builtin_nontemporal_load((const u32x2*)(yr + lane * 4 + 256 * j)); }
;             }
.LBB0_149:
	s_mul_hi_i32 s6, s19, 0x78787879
	s_lshr_b32 s7, s6, 31
	s_ashr_i32 s6, s6, 11
	s_add_i32 s6, s6, s7
	s_mul_i32 s7, s6, 0xffffef00
	s_add_i32 s7, s19, s7
	s_cmpk_gt_i32 s7, 0xff
	s_cselect_b64 s[50:51], -1, 0
	s_add_i32 s8, s44, s19
	s_cmp_lt_i32 s8, 0x8800
	s_cbranch_scc0 .Lr3_slow
	s_mul_hi_i32 s9, s8, 0x78787879
	s_lshr_b32 s25, s9, 31
	s_ashr_i32 s9, s9, 11
	s_add_i32 s9, s9, s25
	s_mul_i32 s25, s9, 0xffffef00
	s_add_i32 s25, s8, s25
	s_cmpk_gt_i32 s25, 0xff
	s_cselect_b64 s[52:53], -1, 0
	s_cmp_lg_u64 s[4:5], 0
	s_cbranch_scc0 .Lr3_slow_u
	v_lshlrev_b32_e32 v160, 2, v36
	s_add_i32 s72, s7, 0xffffff00
	s_cmp_lg_u64 s[50:51], 0
	s_cselect_b32 s27, s22, s49
	s_cselect_b32 s32, s23, s55
	s_cselect_b32 s37, 24, 20
	s_cselect_b32 s72, s72, s7
	s_cselect_b32 s85, s6, 8
	s_mov_b32 s40, s6
	s_mov_b32 s41, 0
	s_lshl_b64 s[40:41], s[40:41], s37
	s_add_u32 s40, s27, s40
	s_addc_u32 s41, s32, s41
	s_lshl_b32 s72, s72, 12
	s_add_u32 s40, s40, s72
	s_addc_u32 s41, s41, 0
	s_add_i32 s27, s85, s3
	s_mul_hi_i32 s32, s27, 0x6000
	s_mulk_i32 s27, 0x6000
	s_add_u32 s66, s34, s27
	s_addc_u32 s67, s35, s32
	s_add_u32 s66, s66, 0x5000
	s_addc_u32 s67, s67, 0
	s_add_i32 s27, s85, s13
	s_mul_hi_i32 s32, s27, 0x6000
	s_mulk_i32 s27, 0x6000
	s_add_u32 s38, s34, s27
	s_addc_u32 s39, s35, s32
	s_add_u32 s46, s38, 0x1000
	s_addc_u32 s47, s39, 0
	s_cmp_lg_u32 s99, 0
	s_cbranch_scc1 .Lr3_slow_pfa
	global_load_dwordx4 v[12:15], v160, s[40:41] nt
	global_load_dwordx4 v[8:11], v160, s[40:41] offset:1024 nt
	global_load_dwordx4 v[4:7], v160, s[40:41] offset:2048 nt
	global_load_dwordx4 v[0:3], v160, s[40:41] offset:3072 nt
	global_load_dwordx2 v[54:55], v[46:47], off offset:-1536 nt
	global_load_dwordx2 v[52:53], v[46:47], off offset:-1024 nt
	global_load_dwordx2 v[50:51], v[46:47], off offset:-512 nt
	global_load_dwordx2 v[48:49], v[46:47], off nt
.Lr3_slow_pfa:
	s_mov_b32 s6, s8
	s_ashr_i32 s7, s8, 31
	s_lshl_b64 s[6:7], s[6:7], 11
	v_lshl_add_u64 v[250:251], v[38:39], 0, s[6:7]
	v_lshl_add_u64 v[252:253], v[40:41], 0, s[6:7]
	s_mov_b64 s[6:7], s[52:53]
	s_add_i32 s72, s25, 0xffffff00
	s_cmp_lg_u64 s[6:7], 0
	s_cselect_b32 s27, s22, s49
	s_cselect_b32 s32, s23, s55
	s_cselect_b32 s37, 24, 20
	s_cselect_b32 s72, s72, s25
	s_cselect_b32 s85, s9, 8
	s_mov_b32 s64, s9
	s_mov_b32 s65, 0
	s_lshl_b64 s[64:65], s[64:65], s37
	s_add_u32 s64, s27, s64
	s_addc_u32 s65, s32, s65
	s_lshl_b32 s72, s72, 12
	s_add_u32 s64, s64, s72
	s_addc_u32 s65, s65, 0
	s_add_i32 s27, s85, s3
	s_mul_hi_i32 s32, s27, 0x6000
	s_mulk_i32 s27, 0x6000
	s_add_u32 s10, s34, s27
	s_addc_u32 s11, s35, s32
	s_add_u32 s10, s10, 0x5000
	s_addc_u32 s11, s11, 0
	s_add_i32 s27, s85, s13
	s_mul_hi_i32 s32, s27, 0x6000
	s_mulk_i32 s27, 0x6000
	s_add_u32 s50, s34, s27
	s_addc_u32 s51, s35, s32
	s_add_u32 s52, s50, 0x1000
	s_addc_u32 s53, s51, 0
	s_cmp_lg_u32 s99, 0
	s_cbranch_scc1 .Lr3_slow_pf
	s_and_b32 s72, s19, 7
	s_and_b32 s85, s72, 3
	s_lshl_b32 s85, s85, 10
	s_lshl_b32 s37, s72, 10
	s_add_i32 s37, s37, s93
	s_cmp_lt_u32 s72, 4
	s_cselect_b32 s6, s66, s38
	s_cselect_b32 s7, s67, s39
	s_cselect_b32 s8, s46, s10
	s_cselect_b32 s9, s47, s11
	s_cselect_b32 s26, s50, s52
	s_cselect_b32 s27, s51, s53
	s_add_u32 s6, s6, s85
	s_addc_u32 s7, s7, 0
	s_add_u32 s8, s8, s85
	s_addc_u32 s9, s9, 0
	s_add_u32 s26, s26, s85
	s_addc_u32 s27, s27, 0
	s_mov_b32 m0, s37
	s_nop 0
	global_load_lds_dwordx4 v160, s[6:7]
	s_add_i32 s37, s37, 0x2000
	s_mov_b32 m0, s37
	s_nop 0
	global_load_lds_dwordx4 v160, s[8:9]
	s_add_i32 s37, s37, 0x2000
	s_mov_b32 m0, s37
	s_nop 0
	global_load_lds_dwordx4 v160, s[26:27]
	global_load_dwordx4 v[16:19], v160, s[64:65] nt
	global_load_dwordx4 v[20:23], v160, s[64:65] offset:1024 nt
	global_load_dwordx4 v[24:27], v160, s[64:65] offset:2048 nt
	global_load_dwordx4 v[28:31], v160, s[64:65] offset:3072 nt
	global_load_dwordx2 v[62:63], v[250:251], off nt
	global_load_dwordx2 v[60:61], v[250:251], off offset:512 nt
	global_load_dwordx2 v[58:59], v[250:251], off offset:1024 nt
	global_load_dwordx2 v[56:57], v[250:251], off offset:1536 nt
	s_waitcnt vmcnt(8)
	s_branch .Lr3_slow_proc

; __device__ __forceinline__ unsigned pk2(float lo, float hi) { return pg8::cvt_pk_bf16(lo, hi); }
;     __device__ __forceinline__ void init(int N, int G, int c, int latent_only) { lat = latent_only; b.init(latent_only ? NB * SEQ : M, N, G, c); }
;     __device__ __forceinline__ void init(int c_, unsigned* cnt_) { lat.init(NB * SEQ, FF2, 1, 0); c = c_; cnt = cnt_; }
; __device__ __forceinline__ void row_pass(const RowPass& R, int gw, int ngw, int lane) {
;     ...
;             if (R.init || R.update) {
; #pragma unroll
;                 for (int j = 0; j < 4; ++j) __builtin_nontemporal_store(v[k][j], (f32x4*)(xrow[k] + lane * 4 + 256 * j));
;             }
;             if (R.norm_out) {
;                 float ss = 0.f;
; #pragma unroll
;                 for (int j = 0; j < 4; ++j) ss += (v[k][j][0] * v[k][j][0] + v[k][j][1] * v[k][j][1]) + (v[k][j][2] * v[k][j][2] + v[k][j][3] * v[k][j][3]);
;                 const float rstd = __builtin_amdgcn_rsqf(wave_sum(ss) * (1.0f / DM) + EPS);
;                 const float* shift = R.mod + ((size_t)(R.ln * 9 + bb) * NMOD + R.si) * DM; const float* scale = shift + DM;
;                 bf16* hr = R.H + (size_t)row * DM;
; #pragma unroll
;                 for (int j = 0; j < 4; ++j) { const f32x4 gp = *(const f32x4*)(R.gpre + lane * 4 + 256 * j), sh = *(const f32x4*)(shift + lane * 4 + 256 * j), sc = *(const f32x4*)(scale + lane * 4 + 256 * j);
;                     const f32x4 hv = (v[k][j] * rstd * gp) * (sc + 1.0f) + sh;
;                     u32x2 w; w.x = pk2(hv[0], hv[1]); w.y = pk2(hv[2], hv[3]); *(u32x2*)(hr + lane * 4 + 256 * j) = w; }
;             }
.LBB0_370:
	s_and_b64 s[46:47], s[40:41], exec
	s_cselect_b32 s15, s8, s49
	s_cselect_b32 s3, s9, s55
	s_add_u32 s15, s15, s60
	s_addc_u32 s3, s3, s61
	s_add_u32 s46, s15, s50
	s_addc_u32 s47, s3, s51
	s_mul_i32 s3, s38, 6
	s_and_b64 s[38:39], s[40:41], exec
	s_cselect_b32 s38, s3, 48
	s_ashr_i32 s39, s38, 31
	s_lshl_b64 s[38:39], s[38:39], 12
	s_add_u32 s38, s34, s38
	s_addc_u32 s39, s35, s39
	s_add_u32 s84, s38, 0x1000
	s_addc_u32 s85, s39, 0
	global_load_dwordx4 v[172:175], v160, s[84:85]
	global_load_dwordx4 v[176:179], v160, s[38:39]
	global_load_dwordx4 v[180:183], v160, s[84:85] offset:1024
	global_load_dwordx4 v[184:187], v160, s[38:39] offset:1024
	global_load_dwordx4 v[188:191], v160, s[84:85] offset:2048
	global_load_dwordx4 v[192:195], v160, s[38:39] offset:2048
	global_load_dwordx4 v[196:199], v160, s[84:85] offset:3072
	global_load_dwordx4 v[218:221], v160, s[38:39] offset:3072
	s_and_b64 s[64:65], s[16:17], exec
	s_cselect_b32 s25, s8, s49
	s_cselect_b32 s3, s9, s55
	s_add_u32 s25, s25, s26
	s_addc_u32 s3, s3, s27
	s_add_u32 s64, s25, s22
	s_addc_u32 s65, s3, s23
	s_mul_i32 s3, s14, 6
	s_and_b64 s[62:63], s[16:17], exec
	s_cselect_b32 s62, s3, 48
	s_ashr_i32 s63, s62, 31
	s_lshl_b64 s[62:63], s[62:63], 12
	s_add_u32 s62, s34, s62
	s_addc_u32 s63, s35, s63
	s_add_u32 s60, s62, 0x1000
	s_addc_u32 s61, s63, 0
	global_load_dwordx4 v[222:225], v160, s[60:61]
	global_load_dwordx4 v[226:229], v160, s[62:63]
	global_load_dwordx4 v[230:233], v160, s[60:61] offset:1024
	global_load_dwordx4 v[234:237], v160, s[62:63] offset:1024
	global_load_dwordx4 v[44:47], v160, s[60:61] offset:2048
	global_load_dwordx4 v[48:51], v160, s[62:63] offset:2048
	global_load_dwordx4 v[52:55], v160, s[60:61] offset:3072
	global_load_dwordx4 v[164:167], v160, s[62:63] offset:3072
	s_and_b64 vcc, exec, s[20:21]
	s_cbranch_vccnz .Lr1_nocopy
	s_waitcnt vmcnt(23)
	global_store_dwordx4 v160, v[28:31], s[46:47] nt
	s_waitcnt vmcnt(23)
	global_store_dwordx4 v160, v[24:27], s[46:47] offset:1024 nt
	s_waitcnt vmcnt(23)
	global_store_dwordx4 v160, v[20:23], s[46:47] offset:2048 nt
	s_waitcnt vmcnt(23)
	global_store_dwordx4 v160, v[16:19], s[46:47] offset:3072 nt
.Lr1_nocopy:
	s_waitcnt vmcnt(20)
	v_pk_mul_f32 v[58:59], v[30:31], v[30:31]
	v_pk_mul_f32 v[60:61], v[28:29], v[28:29]
	v_mul_f32_e32 v43, v16, v16
	v_pk_mov_b32 v[62:63], v[60:61], v[58:59] op_sel:[1,0]
	v_mov_b32_e32 v61, v59
	v_pk_add_f32 v[58:59], v[62:63], v[60:61]
	v_pk_mul_f32 v[60:61], v[26:27], v[26:27]
	v_pk_mul_f32 v[62:63], v[24:25], v[24:25]
	v_pk_add_f32 v[58:59], v[58:59], v[58:59] op_sel:[0,1] op_sel_hi:[1,0]
	v_pk_mov_b32 v[64:65], v[62:63], v[60:61] op_sel:[1,0]
	v_mov_b32_e32 v63, v61
	v_pk_add_f32 v[60:61], v[64:65], v[62:63]
	v_mul_f32_e32 v62, v17, v17
	v_pk_add_f32 v[60:61], v[60:61], v[60:61] op_sel:[0,1] op_sel_hi:[1,0]
	v_mov_b32_e32 v59, v43
	v_mov_b32_e32 v61, v62
	v_pk_add_f32 v[58:59], v[58:59], v[60:61]
	v_mul_f32_e32 v60, v21, v21
	v_mul_f32_e32 v63, v18, v18
	v_pk_fma_f32 v[60:61], v[20:21], v[20:21], v[60:61] op_sel_hi:[1,1,0]
	v_mul_f32_e32 v62, v23, v23
	v_mul_f32_e32 v64, v19, v19
	v_mov_b32_e32 v61, v63
	v_pk_fma_f32 v[62:63], v[22:23], v[22:23], v[62:63] op_sel_hi:[1,1,0]
	s_nop 0
	v_mov_b32_e32 v63, v64
	v_pk_add_f32 v[60:61], v[60:61], v[62:63]
	s_nop 0
	v_pk_add_f32 v[58:59], v[58:59], v[60:61]
	s_nop 0
	v_add_f32_e32 v43, v58, v59
	ds_bpermute_b32 v58, v33, v43
	s_waitcnt lgkmcnt(0)
	v_add_f32_e32 v43, v43, v58
	ds_bpermute_b32 v58, v38, v43
	s_waitcnt lgkmcnt(0)
	v_add_f32_e32 v43, v43, v58
	ds_bpermute_b32 v58, v39, v43
	s_waitcnt lgkmcnt(0)
	v_add_f32_e32 v43, v43, v58
	ds_bpermute_b32 v58, v40, v43
	s_waitcnt lgkmcnt(0)
	v_add_f32_e32 v43, v43, v58
	ds_bpermute_b32 v58, v41, v43
	s_waitcnt lgkmcnt(0)
	v_add_f32_e32 v43, v43, v58
	ds_bpermute_b32 v60, v42, v43
	v_lshl_add_u64 v[58:59], s[10:11], 0, v[36:37]
	v_add_co_u32_e32 v58, vcc, s95, v58
	s_waitcnt lgkmcnt(0)
	v_add_f32_e32 v43, v43, v60
	v_fmamk_f32 v43, v43, 0x3a800000, v200
	v_rsq_f32_e32 v60, v43
	v_addc_co_u32_e32 v59, vcc, 0, v59, vcc
	s_andn2_b64 vcc, exec, s[20:21]
	v_pk_mul_f32 v[28:29], v[28:29], v[60:61] op_sel_hi:[1,0]
	v_pk_mul_f32 v[30:31], v[30:31], v[60:61] op_sel_hi:[1,0]
	v_pk_mul_f32 v[28:29], v[238:239], v[28:29]
	v_pk_mul_f32 v[30:31], v[240:241], v[30:31]
	s_waitcnt vmcnt(14)
	v_pk_add_f32 v[172:173], v[172:173], 1.0 op_sel_hi:[1,0]
	v_pk_add_f32 v[174:175], v[174:175], 1.0 op_sel_hi:[1,0]
	v_pk_fma_f32 v[28:29], v[172:173], v[28:29], v[176:177]
	v_pk_fma_f32 v[30:31], v[174:175], v[30:31], v[178:179]
	v_cvt_pk_bf16_f32 v28, v28, v29
	s_nop 0
	v_cvt_pk_bf16_f32 v29, v30, v31
	global_store_dwordx2 v[58:59], v[28:29], off
	v_pk_mul_f32 v[24:25], v[24:25], v[60:61] op_sel_hi:[1,0]
	v_pk_mul_f32 v[26:27], v[26:27], v[60:61] op_sel_hi:[1,0]
	v_pk_mul_f32 v[24:25], v[242:243], v[24:25]
	v_pk_mul_f32 v[26:27], v[244:245], v[26:27]
	s_waitcnt vmcnt(13)
	v_pk_add_f32 v[180:181], v[180:181], 1.0 op_sel_hi:[1,0]
	v_pk_add_f32 v[182:183], v[182:183], 1.0 op_sel_hi:[1,0]
	v_pk_fma_f32 v[24:25], v[180:181], v[24:25], v[184:185]
	v_pk_fma_f32 v[26:27], v[182:183], v[26:27], v[186:187]
	v_cvt_pk_bf16_f32 v24, v24, v25
	s_nop 0
	v_cvt_pk_bf16_f32 v25, v26, v27
	global_store_dwordx2 v[58:59], v[24:25], off offset:512
	v_pk_mul_f32 v[20:21], v[20:21], v[60:61] op_sel_hi:[1,0]
	v_pk_mul_f32 v[22:23], v[22:23], v[60:61] op_sel_hi:[1,0]
	v_pk_mul_f32 v[20:21], v[246:247], v[20:21]
	v_pk_mul_f32 v[22:23], v[248:249], v[22:23]
	s_waitcnt vmcnt(12)
	v_pk_add_f32 v[188:189], v[188:189], 1.0 op_sel_hi:[1,0]
	v_pk_add_f32 v[190:191], v[190:191], 1.0 op_sel_hi:[1,0]
	v_pk_fma_f32 v[20:21], v[188:189], v[20:21], v[192:193]
	v_pk_fma_f32 v[22:23], v[190:191], v[22:23], v[194:195]
	v_cvt_pk_bf16_f32 v20, v20, v21
	s_nop 0
	v_cvt_pk_bf16_f32 v21, v22, v23
	global_store_dwordx2 v[58:59], v[20:21], off offset:1024
	v_pk_mul_f32 v[16:17], v[16:17], v[60:61] op_sel_hi:[1,0]
	v_pk_mul_f32 v[18:19], v[18:19], v[60:61] op_sel_hi:[1,0]
	v_pk_mul_f32 v[16:17], v[250:251], v[16:17]
	v_pk_mul_f32 v[18:19], v[252:253], v[18:19]
	s_waitcnt vmcnt(11)
	v_pk_add_f32 v[196:197], v[196:197], 1.0 op_sel_hi:[1,0]
	v_pk_add_f32 v[198:199], v[198:199], 1.0 op_sel_hi:[1,0]
	v_pk_fma_f32 v[16:17], v[196:197], v[16:17], v[218:219]
	v_pk_fma_f32 v[18:19], v[198:199], v[18:19], v[220:221]
	v_cvt_pk_bf16_f32 v16, v16, v17
	s_nop 0
	v_cvt_pk_bf16_f32 v17, v18, v19
	global_store_dwordx2 v[58:59], v[16:17], off offset:1536
	s_cbranch_vccnz .Lr1_binv
; __device__ __forceinline__ unsigned pk2(float lo, float hi) { return pg8::cvt_pk_bf16(lo, hi); }
; __device__ __forceinline__ void row_pass(const RowPass& R, int gw, int ngw, int lane) {
;     ...
;             if (R.norm_out) {
;                 float ss = 0.f;
; #pragma unroll
;                 for (int j = 0; j < 4; ++j) ss += (v[k][j][0] * v[k][j][0] + v[k][j][1] * v[k][j][1]) + (v[k][j][2] * v[k][j][2] + v[k][j][3] * v[k][j][3]);
;                 const float rstd = __builtin_amdgcn_rsqf(wave_sum(ss) * (1.0f / DM) + EPS);
;                 const float* shift = R.mod + ((size_t)(R.ln * 9 + bb) * NMOD + R.si) * DM; const float* scale = shift + DM;
;                 bf16* hr = R.H + (size_t)row * DM;
; #pragma unroll
;                 for (int j = 0; j < 4; ++j) { const f32x4 gp = *(const f32x4*)(R.gpre + lane * 4 + 256 * j), sh = *(const f32x4*)(shift + lane * 4 + 256 * j), sc = *(const f32x4*)(scale + lane * 4 + 256 * j);
;                     const f32x4 hv = (v[k][j] * rstd * gp) * (sc + 1.0f) + sh;
;                     u32x2 w; w.x = pk2(hv[0], hv[1]); w.y = pk2(hv[2], hv[3]); *(u32x2*)(hr + lane * 4 + 256 * j) = w; }
;             }
	v_pk_mul_f32 v[58:59], v[2:3], v[2:3]
	v_pk_mul_f32 v[60:61], v[0:1], v[0:1]
	v_mul_f32_e32 v43, v12, v12
	v_pk_mov_b32 v[62:63], v[60:61], v[58:59] op_sel:[1,0]
	v_mov_b32_e32 v61, v59
	v_pk_add_f32 v[58:59], v[62:63], v[60:61]
	v_pk_mul_f32 v[60:61], v[6:7], v[6:7]
	v_pk_mul_f32 v[62:63], v[4:5], v[4:5]
	v_pk_add_f32 v[58:59], v[58:59], v[58:59] op_sel:[0,1] op_sel_hi:[1,0]
	v_pk_mov_b32 v[64:65], v[62:63], v[60:61] op_sel:[1,0]
	v_mov_b32_e32 v63, v61
	v_pk_add_f32 v[60:61], v[64:65], v[62:63]
	v_mul_f32_e32 v62, v13, v13
	v_pk_add_f32 v[60:61], v[60:61], v[60:61] op_sel:[0,1] op_sel_hi:[1,0]
	v_mov_b32_e32 v59, v43
	v_mov_b32_e32 v61, v62
	v_pk_add_f32 v[58:59], v[58:59], v[60:61]
	v_mul_f32_e32 v60, v9, v9
	v_mul_f32_e32 v63, v14, v14
	v_pk_fma_f32 v[60:61], v[8:9], v[8:9], v[60:61] op_sel_hi:[1,1,0]
	v_mul_f32_e32 v62, v11, v11
	v_mul_f32_e32 v64, v15, v15
	v_mov_b32_e32 v61, v63
	v_pk_fma_f32 v[62:63], v[10:11], v[10:11], v[62:63] op_sel_hi:[1,1,0]
	s_nop 0
	v_mov_b32_e32 v63, v64
	v_pk_add_f32 v[60:61], v[60:61], v[62:63]
	s_nop 0
	v_pk_add_f32 v[58:59], v[58:59], v[60:61]
	s_nop 0
	v_add_f32_e32 v43, v58, v59
	ds_bpermute_b32 v58, v33, v43
	s_waitcnt lgkmcnt(0)
	v_add_f32_e32 v43, v43, v58
	ds_bpermute_b32 v58, v38, v43
	s_waitcnt lgkmcnt(0)
	v_add_f32_e32 v43, v43, v58
	ds_bpermute_b32 v58, v39, v43
	s_waitcnt lgkmcnt(0)
	v_add_f32_e32 v43, v43, v58
	ds_bpermute_b32 v58, v40, v43
	s_waitcnt lgkmcnt(0)
	v_add_f32_e32 v43, v43, v58
	ds_bpermute_b32 v58, v41, v43
	s_waitcnt lgkmcnt(0)
	v_add_f32_e32 v43, v43, v58
	ds_bpermute_b32 v60, v42, v43
	v_lshl_add_u64 v[58:59], s[12:13], 0, v[36:37]
	v_add_co_u32_e32 v58, vcc, s95, v58
	s_waitcnt lgkmcnt(0)
	v_add_f32_e32 v43, v43, v60
	v_fmamk_f32 v43, v43, 0x3a800000, v200
	v_rsq_f32_e32 v60, v43
	v_addc_co_u32_e32 v59, vcc, 0, v59, vcc
	s_nop 0
	v_pk_mul_f32 v[0:1], v[0:1], v[60:61] op_sel_hi:[1,0]
	v_pk_mul_f32 v[2:3], v[2:3], v[60:61] op_sel_hi:[1,0]
	v_pk_mul_f32 v[0:1], v[238:239], v[0:1]
	v_pk_mul_f32 v[2:3], v[240:241], v[2:3]
	s_waitcnt vmcnt(10)
	v_pk_add_f32 v[222:223], v[222:223], 1.0 op_sel_hi:[1,0]
	v_pk_add_f32 v[224:225], v[224:225], 1.0 op_sel_hi:[1,0]
	v_pk_fma_f32 v[0:1], v[222:223], v[0:1], v[226:227]
	v_pk_fma_f32 v[2:3], v[224:225], v[2:3], v[228:229]
	v_cvt_pk_bf16_f32 v0, v0, v1
	s_nop 0
	v_cvt_pk_bf16_f32 v1, v2, v3
	global_store_dwordx2 v[58:59], v[0:1], off
	v_pk_mul_f32 v[4:5], v[4:5], v[60:61] op_sel_hi:[1,0]
	v_pk_mul_f32 v[6:7], v[6:7], v[60:61] op_sel_hi:[1,0]
	v_pk_mul_f32 v[4:5], v[242:243], v[4:5]
	v_pk_mul_f32 v[6:7], v[244:245], v[6:7]
	s_waitcnt vmcnt(9)
	v_pk_add_f32 v[230:231], v[230:231], 1.0 op_sel_hi:[1,0]
	v_pk_add_f32 v[232:233], v[232:233], 1.0 op_sel_hi:[1,0]
	v_pk_fma_f32 v[4:5], v[230:231], v[4:5], v[234:235]
	v_pk_fma_f32 v[6:7], v[232:233], v[6:7], v[236:237]
	v_cvt_pk_bf16_f32 v4, v4, v5
	s_nop 0
	v_cvt_pk_bf16_f32 v5, v6, v7
	global_store_dwordx2 v[58:59], v[4:5], off offset:512
	v_pk_mul_f32 v[8:9], v[8:9], v[60:61] op_sel_hi:[1,0]
	v_pk_mul_f32 v[10:11], v[10:11], v[60:61] op_sel_hi:[1,0]
	v_pk_mul_f32 v[8:9], v[246:247], v[8:9]
	v_pk_mul_f32 v[10:11], v[248:249], v[10:11]
	s_waitcnt vmcnt(8)
	v_pk_add_f32 v[44:45], v[44:45], 1.0 op_sel_hi:[1,0]
	v_pk_add_f32 v[46:47], v[46:47], 1.0 op_sel_hi:[1,0]
	v_pk_fma_f32 v[8:9], v[44:45], v[8:9], v[48:49]
	v_pk_fma_f32 v[10:11], v[46:47], v[10:11], v[50:51]
	v_cvt_pk_bf16_f32 v8, v8, v9
	s_nop 0
	v_cvt_pk_bf16_f32 v9, v10, v11
	global_store_dwordx2 v[58:59], v[8:9], off offset:1024
	v_pk_mul_f32 v[12:13], v[12:13], v[60:61] op_sel_hi:[1,0]
	v_pk_mul_f32 v[14:15], v[14:15], v[60:61] op_sel_hi:[1,0]
	v_pk_mul_f32 v[12:13], v[250:251], v[12:13]
	v_pk_mul_f32 v[14:15], v[252:253], v[14:15]
	s_waitcnt vmcnt(7)
	v_pk_add_f32 v[52:53], v[52:53], 1.0 op_sel_hi:[1,0]
	v_pk_add_f32 v[54:55], v[54:55], 1.0 op_sel_hi:[1,0]
	v_pk_fma_f32 v[12:13], v[52:53], v[12:13], v[164:165]
	v_pk_fma_f32 v[14:15], v[54:55], v[14:15], v[166:167]
	v_cvt_pk_bf16_f32 v12, v12, v13
	s_nop 0
	v_cvt_pk_bf16_f32 v13, v14, v15
	global_store_dwordx2 v[58:59], v[12:13], off offset:1536
	s_branch .LBB0_367
